# x17 + prologue de-serialisation of the ctx-attention unit (Q-tail and first K/V tile loads in flight together)
# speedup vs baseline: 1.0040x; 1.0040x over previous
; #define LAS __attribute__((address_space(3)))
; __device__ __forceinline__ int v_st(int k, int c) { const int kk = (k & ~0xC) | ((k & 4) << 1) | ((k & 8) >> 1); return ((kk >> 3) * 4 + (c >> 5)) * 512 + ((kk & 7) * 32 + (c & 31)) * 2; }
; #define SLOAD(kt) do { SLOADV(kt); SLOADK(kt); } while (0)
; #define SWAIT() asm volatile("s_waitcnt vmcnt(0)" ::: "memory")
; __device__ __forceinline__ void qkt(f32x16& p0, f32x16& p1, const LAS unsigned char* Ks, const bf16x8* qr, const LAS unsigned char* qrp, int qsw, const int (&kq)[4], int hi) {
;     p0 = f32x16{}; p1 = f32x16{};
; #pragma unroll
;     for (int d0 = 0; d0 < 12; ++d0) {
;         const bf16x8 b0 = *(const LAS bf16x8*)(Ks + kq[d0 & 3] + 128 * (d0 >> 2));
;         const bf16x8 b1 = *(const LAS bf16x8*)(Ks + kq[d0 & 3] + 128 * (d0 >> 2) + 32 * 384);
;         bf16x8 qv; if (d0 < 8) qv = qr[d0]; else qv = *(const LAS bf16x8*)(qrp + (((2 * (d0 - 8) + hi) ^ qsw) << 4));
;         p0 = __builtin_amdgcn_mfma_f32_32x32x16_bf16(b0, qv, p0, 0, 0, 0);
;         p1 = __builtin_amdgcn_mfma_f32_32x32x16_bf16(b1, qv, p1, 0, 0, 0); }
; }
; template <bool DIRECT> ...
;     ...
;     const bf16_t* Qw = QKV + (size_t)(qrow0 + wid * QBLK + r32) * NUP + h * 192 + hi * 8;
; #pragma unroll
;     for (int d0 = 0; d0 < 8; ++d0) qr[d0] = *(const bf16x8*)(Qw + d0 * 16);
;     LAS unsigned char* qrp = lds + OFF_QR + wid * 4096 + r32 * 128; const int qsw = (r32 >> 1) & 7;
;     int kq[4];
; #pragma unroll
;     for (int q = 0; q < 4; ++q) kq[q] = 384 * r32 + (((2 * q + hi) ^ qsw) << 4);
; #pragma unroll
;     for (int d0 = 8; d0 < 12; ++d0) *(LAS bf16x8*)(qrp + (((2 * (d0 - 8) + hi) ^ qsw) << 4)) = *(const bf16x8*)(Qw + d0 * 16);
;     const int sr = tid >> 4, sc = (tid & 15) * 8;
;     const int vst0 = v_st(sr, sc);
;     const int kst0 = KSWZ(sr, sc * 2);
;     const int krst = KSWZ(tid >> 3, 256 + (tid & 7) * 16);
;     const unsigned voffV = (unsigned)(sr * NUP + sc) * 2u, voffR = (unsigned)((tid >> 3) * INWP + (tid & 7) * 8) * 2u;
;     const char* Vb = (const char*)(QKV + 768 + h * 256 + 128); const char* Kb = (const char*)(QKV + 768 + h * 256); const char* Rb = (const char*)(Z + ZKR);
;     const int vb0 = (int)(uintptr_t)V_lds + v_rd_base(lane);
;     bf16x8 vs0, vs1, ks0, ks1, ks2;
;     ...
;     f32x16 pA0, pA1, pB0, pB1; float mnA, mnB, alA, alB; bf16x8 pa0, pa1, pa2, pa3;
;     SLOAD(0); SWAIT(); SWRITE(0); __syncthreads();
.LBB0_957:
	s_and_b32 s19, s50, 0x100
	s_bitset1_b32 s19, 13
	v_add_u32_e32 v209, s19, v182
	s_and_b32 s18, s17, 3
	v_or_b32_e32 v2, v209, v180
	v_mov_b64_e32 v[0:1], s[44:45]
	v_mad_i64_i32 v[0:1], s[20:21], v2, s13, v[0:1]
	s_mul_i32 s76, s18, 0x180
	v_lshl_add_u64 v[0:1], v[0:1], 0, s[76:77]
	v_lshl_add_u64 v[4:5], v[0:1], 0, v[96:97]
	global_load_dwordx4 v[126:129], v[4:5], off
	global_load_dwordx4 v[122:125], v[4:5], off offset:32
	global_load_dwordx4 v[118:121], v[4:5], off offset:64
	global_load_dwordx4 v[114:117], v[4:5], off offset:96
	global_load_dwordx4 v[110:113], v[4:5], off offset:128
	global_load_dwordx4 v[106:109], v[4:5], off offset:160
	global_load_dwordx4 v[102:105], v[4:5], off offset:192
	global_load_dwordx4 v[98:101], v[4:5], off offset:224
	global_load_dwordx4 v[0:3], v[4:5], off offset:256
	global_load_dwordx4 v[80:83], v[4:5], off offset:288
	global_load_dwordx4 v[84:87], v[4:5], off offset:320
	global_load_dwordx4 v[88:91], v[4:5], off offset:352
	v_add_u32_e32 v213, v191, v183
	v_add_u32_e32 v212, v191, v185
	v_add_u32_e32 v211, v191, v187
	s_lshl_b32 s20, s18, 9
	s_add_u32 s42, s48, s20
	s_addc_u32 s43, s49, 0
	s_mul_i32 s20, s19, 0xe00
	s_mul_hi_i32 s21, s19, 0xe00
	s_add_u32 s22, s42, s20
	s_addc_u32 s23, s43, s21
	v_lshl_add_u64 v[8:9], s[22:23], 0, v[174:175]
	s_mov_b32 s25, 0x1c000
	v_add_u32_e32 v210, v191, v189
	v_add_co_u32_e32 v12, vcc, s25, v8
	v_mad_i64_i32 v[16:17], s[22:23], s19, v218, v[176:177]
	s_nop 0
	v_addc_co_u32_e32 v13, vcc, 0, v9, vcc
	v_add_u32_e32 v225, 0, v192
	v_add_u32_e32 v226, 0, v193
	v_add_u32_e32 v222, 0, v184
	v_add_u32_e32 v224, 0, v186
	v_add_u32_e32 v223, 0, v188
	v_add_u32_e32 v221, 0, v190
	v_lshl_add_u64 v[146:147], s[42:43], 0, v[174:175]
	global_load_dwordx4 v[92:95], v[8:9], off offset:256
	global_load_dwordx4 v[4:7], v[12:13], off offset:256
	s_nop 0
	global_load_dwordx4 v[8:11], v[8:9], off
	s_nop 0
	global_load_dwordx4 v[12:15], v[12:13], off
	s_nop 0
	global_load_dwordx4 v[16:19], v[16:17], off
	s_waitcnt vmcnt(5)
	ds_write_b128 v213, v[0:3]
	ds_write_b128 v212, v[80:83]
	ds_write_b128 v211, v[84:87]
	ds_write_b128 v210, v[88:91]
	s_waitcnt vmcnt(4)
	ds_write_b128 v208, v[92:95]
	s_waitcnt vmcnt(3)
	ds_write_b128 v208, v[4:7] offset:8192
	s_waitcnt vmcnt(2)
	ds_write_b128 v225, v[8:11] offset:49152
	s_waitcnt vmcnt(1)
	ds_write_b128 v225, v[12:15] offset:61440
	s_waitcnt vmcnt(0)
	ds_write_b128 v226, v[16:19] offset:49152
	s_waitcnt lgkmcnt(0)
	s_barrier
	ds_read_b128 v[0:3], v222 offset:49152
	ds_read_b128 v[4:7], v222 offset:61440
	s_waitcnt lgkmcnt(1)
	v_mfma_f32_32x32x16_bf16 v[16:31], v[0:3], v[126:129], 0
	ds_read_b128 v[32:35], v224 offset:49152
	ds_read_b128 v[36:39], v224 offset:61440
	s_waitcnt lgkmcnt(2)
	v_mfma_f32_32x32x16_bf16 v[0:15], v[4:7], v[126:129], 0
	s_waitcnt lgkmcnt(1)
	v_mfma_f32_32x32x16_bf16 v[16:31], v[32:35], v[122:125], v[16:31]
	s_waitcnt lgkmcnt(0)
	v_mfma_f32_32x32x16_bf16 v[0:15], v[36:39], v[122:125], v[0:15]
	ds_read_b128 v[32:35], v223 offset:49152
	ds_read_b128 v[36:39], v223 offset:61440
	s_waitcnt lgkmcnt(1)
	v_mfma_f32_32x32x16_bf16 v[16:31], v[32:35], v[118:121], v[16:31]
	s_waitcnt lgkmcnt(0)
	v_mfma_f32_32x32x16_bf16 v[0:15], v[36:39], v[118:121], v[0:15]
	ds_read_b128 v[32:35], v221 offset:49152
	ds_read_b128 v[36:39], v221 offset:61440
	s_waitcnt lgkmcnt(1)
	v_mfma_f32_32x32x16_bf16 v[16:31], v[32:35], v[114:117], v[16:31]
	s_waitcnt lgkmcnt(0)
	v_mfma_f32_32x32x16_bf16 v[0:15], v[36:39], v[114:117], v[0:15]
	ds_read_b128 v[32:35], v222 offset:49280
	ds_read_b128 v[36:39], v222 offset:61568
	s_waitcnt lgkmcnt(1)
	v_mfma_f32_32x32x16_bf16 v[16:31], v[32:35], v[110:113], v[16:31]
	s_waitcnt lgkmcnt(0)
	v_mfma_f32_32x32x16_bf16 v[0:15], v[36:39], v[110:113], v[0:15]
	ds_read_b128 v[32:35], v224 offset:49280
	ds_read_b128 v[36:39], v224 offset:61568
	s_waitcnt lgkmcnt(1)
	v_mfma_f32_32x32x16_bf16 v[16:31], v[32:35], v[106:109], v[16:31]
	s_waitcnt lgkmcnt(0)
	v_mfma_f32_32x32x16_bf16 v[0:15], v[36:39], v[106:109], v[0:15]
	ds_read_b128 v[32:35], v223 offset:49280
	ds_read_b128 v[36:39], v223 offset:61568
	s_waitcnt lgkmcnt(1)
	v_mfma_f32_32x32x16_bf16 v[16:31], v[32:35], v[102:105], v[16:31]
	s_waitcnt lgkmcnt(0)
	v_mfma_f32_32x32x16_bf16 v[0:15], v[36:39], v[102:105], v[0:15]
	ds_read_b128 v[32:35], v221 offset:49280
	ds_read_b128 v[36:39], v221 offset:61568
	s_waitcnt lgkmcnt(1)
	v_mfma_f32_32x32x16_bf16 v[16:31], v[32:35], v[98:101], v[16:31]
	s_waitcnt lgkmcnt(0)
	v_mfma_f32_32x32x16_bf16 v[0:15], v[36:39], v[98:101], v[0:15]
	ds_read_b128 v[32:35], v222 offset:49408
	ds_read_b128 v[36:39], v222 offset:61696
	ds_read_b128 v[40:43], v213
	s_waitcnt lgkmcnt(0)
	v_mfma_f32_32x32x16_bf16 v[16:31], v[32:35], v[40:43], v[16:31]
	v_mfma_f32_32x32x16_bf16 v[0:15], v[36:39], v[40:43], v[0:15]
	ds_read_b128 v[32:35], v224 offset:49408
	ds_read_b128 v[36:39], v224 offset:61696
	ds_read_b128 v[40:43], v212
	s_waitcnt lgkmcnt(0)
	v_mfma_f32_32x32x16_bf16 v[16:31], v[32:35], v[40:43], v[16:31]
	v_mfma_f32_32x32x16_bf16 v[0:15], v[36:39], v[40:43], v[0:15]
	ds_read_b128 v[32:35], v223 offset:49408
	ds_read_b128 v[36:39], v223 offset:61696
	ds_read_b128 v[40:43], v211
	s_waitcnt lgkmcnt(0)
	v_mfma_f32_32x32x16_bf16 v[16:31], v[32:35], v[40:43], v[16:31]
	v_mfma_f32_32x32x16_bf16 v[0:15], v[36:39], v[40:43], v[0:15]
	ds_read_b128 v[32:35], v221 offset:49408
	ds_read_b128 v[36:39], v221 offset:61696
	ds_read_b128 v[40:43], v210
	s_waitcnt lgkmcnt(0)
; #define SBAR() __builtin_amdgcn_sched_barrier(0)
; #define SLOAD(kt) do { SLOADV(kt); SLOADK(kt); } while (0)
; #define SWRITE(b) do { *(LAS bf16x8*)(V_lds + (b) * SHM_V + vst0) = vs0; *(LAS bf16x8*)(V_lds + (b) * SHM_V + vst0 + 8192) = vs1; \
;     *(LAS bf16x8*)(K_lds + (b) * SHM_K + kst0) = ks0; *(LAS bf16x8*)(K_lds + (b) * SHM_K + kst0 + 32 * 384) = ks1; *(LAS bf16x8*)(K_lds + (b) * SHM_K + krst) = ks2; } while (0)
; #define SWAIT() asm volatile("s_waitcnt vmcnt(0)" ::: "memory")
; __device__ __forceinline__ void partialSM(f32x16& p0, f32x16& p1, float& m_reg, float& mn, float& alpha) {
;     constexpr float C = SCALE * 1.4426950408889634f;
;     float pmax = p0[0];
; #pragma unroll
;     for (int r = 1; r < 16; ++r) pmax = fmaxf(pmax, p0[r]);
; #pragma unroll
;     for (int r = 0; r < 16; ++r) pmax = fmaxf(pmax, p1[r]);
;     { auto rr = __builtin_amdgcn_permlane32_swap(__float_as_uint(pmax), __float_as_uint(pmax), false, false);
;       pmax = fmaxf(__uint_as_float(rr[0]), __uint_as_float(rr[1])); }
;     if (__builtin_expect(__all(pmax - m_reg <= THR / SCALE), 1)) { mn = m_reg; alpha = 1.f; }
;     else { mn = fmaxf(m_reg, pmax); alpha = __builtin_amdgcn_exp2f((m_reg - mn) * C); m_reg = mn; }
;     const float mnC = -mn * C;
; #pragma unroll
;     for (int r = 0; r < 16; ++r) p0[r] = fmaf(p0[r], C, mnC);
; #pragma unroll
;     for (int r = 0; r < 16; ++r) p1[r] = fmaf(p1[r], C, mnC);
; #pragma unroll
;     for (int r = 0; r < 16; ++r) p0[r] = __builtin_amdgcn_exp2f(p0[r]);
; }
; template <bool DIRECT> ...
;     ...
;     qkt(pA0, pA1, K_lds, qr, qrp, qsw, kq, hi); partialSM(pA0, pA1, m_reg, mnA, alA);
;     SLOAD(1);
;     SWAIT(); SWRITE(1); __syncthreads();
;     if (2 < NT) SLOAD(2);
;     int kb = 1;
;     for (int j = 1; j + 1 < NT; j += 2) {
;         { const int pb_ = kb == 0 ? 2 : kb - 1, nb_ = kb == 2 ? 0 : kb + 1;
;         SBAR(); qkt(pB0, pB1, K_lds + kb * SHM_K, qr, qrp, qsw, kq, hi);
;         finishSM(pA0, pA1, alA, l_reg, pa0, pa1, pa2, pa3); SBAR();
;         pv_d0(o, vb0 + pb_ * SHM_V, pa0, pa1, pa2, pa3); partialSM(pB0, pB1, m_reg, mnB, alB);
	v_mfma_f32_32x32x16_bf16 v[16:31], v[32:35], v[40:43], v[16:31]
	v_mfma_f32_32x32x16_bf16 v[0:15], v[36:39], v[40:43], v[0:15]
	s_nop 10
	v_max_f32_e32 v32, v17, v17
	v_max_f32_e32 v33, v16, v16
	v_max_f32_e32 v32, v33, v32
	v_max3_f32 v32, v32, v18, v19
	v_max3_f32 v32, v32, v20, v21
	v_max3_f32 v32, v32, v22, v23
	v_max3_f32 v32, v32, v24, v25
	v_max3_f32 v32, v32, v26, v27
	v_max3_f32 v32, v32, v28, v29
	v_max3_f32 v32, v32, v30, v31
	v_max3_f32 v32, v32, v0, v1
	v_max3_f32 v32, v32, v2, v3
	v_max3_f32 v32, v32, v4, v5
	v_max3_f32 v32, v32, v6, v7
	v_max3_f32 v32, v32, v8, v9
	v_max3_f32 v32, v32, v10, v11
	v_max3_f32 v32, v32, v12, v13
	v_max3_f32 v32, v32, v14, v15
	v_mov_b32_e32 v33, v32
	s_nop 1
	v_permlane32_swap_b32_e32 v32, v33
	v_max_f32_e32 v33, v33, v33
	v_max_f32_e32 v32, v32, v32
	v_max_f32_e32 v32, v32, v33
	v_add_f32_e32 v33, 0x7149f2ca, v32
	v_cmp_ge_f32_e32 vcc, s14, v33
	s_cmp_eq_u64 vcc, exec
	s_cselect_b64 s[40:41], -1, 0
	v_max_f32_e32 v230, 0xf149f2ca, v32
	v_cndmask_b32_e64 v229, v230, v219, s[40:41]
	s_add_i32 s21, s19, 64
	s_add_i32 s22, s20, 0x38000
	v_mul_f32_e32 v32, 0xbdd53b94, v229
	s_mul_hi_i32 s23, s21, 0xe00
	s_add_u32 s22, s42, s22
	v_fmamk_f32 v42, v25, 0x3dd53b94, v32
	v_fmamk_f32 v43, v26, 0x3dd53b94, v32
	s_addc_u32 s23, s43, s23
	v_fmamk_f32 v34, v17, 0x3dd53b94, v32
	v_fmamk_f32 v35, v18, 0x3dd53b94, v32
	v_fmamk_f32 v36, v19, 0x3dd53b94, v32
	v_fmamk_f32 v37, v20, 0x3dd53b94, v32
	v_fmamk_f32 v46, v29, 0x3dd53b94, v32
	v_fmamk_f32 v19, v5, 0x3dd53b94, v32
	v_fmamk_f32 v20, v6, 0x3dd53b94, v32
	v_exp_f32_e32 v5, v42
	v_exp_f32_e32 v6, v43
	v_lshl_add_u64 v[42:43], s[22:23], 0, v[174:175]
	v_fmamk_f32 v33, v16, 0x3dd53b94, v32
	v_fmamk_f32 v44, v27, 0x3dd53b94, v32
	v_fmamk_f32 v47, v30, 0x3dd53b94, v32
	v_fmamk_f32 v27, v1, 0x3dd53b94, v32
	v_fmamk_f32 v25, v11, 0x3dd53b94, v32
	v_fmamk_f32 v16, v12, 0x3dd53b94, v32
	v_fmamk_f32 v17, v13, 0x3dd53b94, v32
	v_fmamk_f32 v18, v14, 0x3dd53b94, v32
	v_exp_f32_e32 v11, v34
	v_exp_f32_e32 v12, v35
	v_exp_f32_e32 v13, v36
	v_exp_f32_e32 v14, v37
	v_exp_f32_e32 v1, v46
	global_load_dwordx4 v[34:37], v[42:43], off offset:256
	v_add_co_u32_e32 v46, vcc, s25, v42
	v_fmamk_f32 v38, v21, 0x3dd53b94, v32
	v_fmamk_f32 v39, v22, 0x3dd53b94, v32
	v_fmamk_f32 v40, v23, 0x3dd53b94, v32
	v_fmamk_f32 v41, v24, 0x3dd53b94, v32
	v_fmamk_f32 v45, v28, 0x3dd53b94, v32
	v_fmamk_f32 v28, v2, 0x3dd53b94, v32
	v_exp_f32_e32 v2, v47
	v_addc_co_u32_e32 v47, vcc, 0, v43, vcc
	v_fmamk_f32 v31, v31, 0x3dd53b94, v32
	v_fmamk_f32 v26, v0, 0x3dd53b94, v32
	v_fmamk_f32 v29, v3, 0x3dd53b94, v32
	v_fmamk_f32 v30, v4, 0x3dd53b94, v32
	v_fmamk_f32 v21, v7, 0x3dd53b94, v32
	v_fmamk_f32 v22, v8, 0x3dd53b94, v32
	v_fmamk_f32 v23, v9, 0x3dd53b94, v32
	v_fmamk_f32 v24, v10, 0x3dd53b94, v32
	v_fmac_f32_e32 v32, 0x3dd53b94, v15
	v_exp_f32_e32 v15, v38
	v_exp_f32_e32 v8, v39
	v_exp_f32_e32 v10, v40
	v_exp_f32_e32 v3, v41
	v_exp_f32_e32 v7, v44
	v_exp_f32_e32 v0, v45
	global_load_dwordx4 v[38:41], v[46:47], off offset:256
	s_nop 0
	global_load_dwordx4 v[42:45], v[42:43], off
	s_nop 0
	global_load_dwordx4 v[46:49], v[46:47], off
	v_mad_i64_i32 v[50:51], s[22:23], s21, v218, v[176:177]
	global_load_dwordx4 v[50:53], v[50:51], off
	s_add_i32 s21, 0, 0x12000
	s_add_i32 s24, s19, 0x80
	s_add_i32 s20, s20, 0x70000
	s_mul_hi_i32 s23, s24, 0xe00
	s_add_u32 s22, s42, s20
	s_addc_u32 s23, s43, s23
	s_waitcnt vmcnt(0)
	s_waitcnt vmcnt(4)
	ds_write_b128 v208, v[34:37] offset:16384
	s_waitcnt vmcnt(3)
	ds_write_b128 v208, v[38:41] offset:24576
	v_lshl_add_u64 v[34:35], s[22:23], 0, v[174:175]
	v_exp_f32_e32 v4, v31
	v_add_u32_e32 v31, s21, v192
	v_add_co_u32_e32 v36, vcc, s25, v34
	s_waitcnt vmcnt(2)
	ds_write_b128 v31, v[42:45]
	s_waitcnt vmcnt(1)
	ds_write_b128 v31, v[46:49] offset:12288
	v_add_u32_e32 v31, s21, v193
	v_addc_co_u32_e32 v37, vcc, 0, v35, vcc
	v_mad_i64_i32 v[38:39], s[22:23], s24, v218, v[176:177]
	s_waitcnt vmcnt(0)
	ds_write_b128 v31, v[50:53]
	s_waitcnt lgkmcnt(0)
	s_barrier
	global_load_dwordx4 v[130:133], v[34:35], off offset:256
	global_load_dwordx4 v[134:137], v[36:37], off offset:256
	global_load_dwordx4 v[158:161], v[38:39], off
	global_load_dwordx4 v[162:165], v[36:37], off
	global_load_dwordx4 v[166:169], v[34:35], off
	v_exp_f32_e32 v9, v33
	v_add_u32_e32 v31, s21, v184
	ds_read_b128 v[34:37], v31
	ds_read_b128 v[38:41], v31 offset:12288
	v_add_u32_e32 v33, s21, v186
	v_add_u32_e32 v46, s21, v188
	v_add_u32_e32 v47, s21, v190
	s_waitcnt lgkmcnt(1)
	v_mfma_f32_32x32x16_bf16 v[80:95], v[34:37], v[126:129], 0
	v_exp_f32_e32 v26, v26
	v_exp_f32_e32 v27, v27
	v_exp_f32_e32 v28, v28
	v_exp_f32_e32 v29, v29
	v_exp_f32_e32 v30, v30
	v_exp_f32_e32 v19, v19
	v_exp_f32_e32 v20, v20
	s_waitcnt lgkmcnt(0)
	v_mfma_f32_32x32x16_bf16 v[64:79], v[38:41], v[126:129], 0
	ds_read_b128 v[34:37], v33
	ds_read_b128 v[38:41], v33 offset:12288
	v_exp_f32_e32 v21, v21
	v_exp_f32_e32 v22, v22
	v_exp_f32_e32 v23, v23
	v_exp_f32_e32 v24, v24
	v_exp_f32_e32 v25, v25
	v_exp_f32_e32 v16, v16
	s_waitcnt lgkmcnt(1)
	v_mfma_f32_32x32x16_bf16 v[80:95], v[34:37], v[122:125], v[80:95]
	v_exp_f32_e32 v17, v17
	v_exp_f32_e32 v18, v18
	s_waitcnt lgkmcnt(0)
	v_mfma_f32_32x32x16_bf16 v[64:79], v[38:41], v[122:125], v[64:79]
	ds_read_b128 v[34:37], v46
	ds_read_b128 v[38:41], v46 offset:12288
	s_waitcnt lgkmcnt(1)
	v_mfma_f32_32x32x16_bf16 v[80:95], v[34:37], v[118:121], v[80:95]
	s_waitcnt lgkmcnt(0)
	v_mfma_f32_32x32x16_bf16 v[64:79], v[38:41], v[118:121], v[64:79]
	ds_read_b128 v[34:37], v47
	ds_read_b128 v[38:41], v47 offset:12288
	s_waitcnt lgkmcnt(1)
	v_mfma_f32_32x32x16_bf16 v[80:95], v[34:37], v[114:117], v[80:95]
	s_waitcnt lgkmcnt(0)
; #define SBAR() __builtin_amdgcn_sched_barrier(0)
; __device__ __forceinline__ void finishSM(f32x16& p0, f32x16& p1, float alpha, float& l_reg, bf16x8& pa0, bf16x8& pa1, bf16x8& pa2, bf16x8& pa3) {
; #pragma unroll
;     for (int r = 0; r < 16; ++r) p1[r] = __builtin_amdgcn_exp2f(p1[r]);
;     float ps = 0;
; #pragma unroll
;     for (int r = 0; r < 16; ++r) ps += p0[r];
; #pragma unroll
;     for (int r = 0; r < 16; ++r) ps += p1[r];
;     { auto rr = __builtin_amdgcn_permlane32_swap(__float_as_uint(ps), __float_as_uint(ps), false, false);
;       ps = __uint_as_float(rr[0]) + __uint_as_float(rr[1]); }
;     l_reg = l_reg * alpha + ps;
;     ...
;     PK4(p0, 0, pa0); PK4(p0, 8, pa1); PK4(p1, 0, pa2); PK4(p1, 8, pa3);
;     ...
; }
; template <int D0> __device__ __forceinline__ void pv_one(f32x16& od, int vb, bf16x8 pa0, bf16x8 pa1, bf16x8 pa2, bf16x8 pa3) {
;     const s16x4 l0 = tr_read<v_rd_off(D0, 0, 0)>(vb), h0 = tr_read<v_rd_off(D0, 0, 1)>(vb), l1 = tr_read<v_rd_off(D0, 1, 0)>(vb), h1 = tr_read<v_rd_off(D0, 1, 1)>(vb);
;     const s16x4 l2 = tr_read<v_rd_off(D0, 2, 0)>(vb), h2 = tr_read<v_rd_off(D0, 2, 1)>(vb), l3 = tr_read<v_rd_off(D0, 3, 0)>(vb), h3 = tr_read<v_rd_off(D0, 3, 1)>(vb);
;     asm volatile("s_waitcnt lgkmcnt(0)" ::: "memory"); SBAR();
;     ...
;     od = __builtin_amdgcn_mfma_f32_32x32x16_bf16(pa0, PK(l0, h0), od, 0, 0, 0);
;     od = __builtin_amdgcn_mfma_f32_32x32x16_bf16(pa1, PK(l1, h1), od, 0, 0, 0);
;     od = __builtin_amdgcn_mfma_f32_32x32x16_bf16(pa2, PK(l2, h2), od, 0, 0, 0);
;     od = __builtin_amdgcn_mfma_f32_32x32x16_bf16(pa3, PK(l3, h3), od, 0, 0, 0);
;     ...
; }
; __device__ __forceinline__ void pv_d0(f32x16* o, int vb, bf16x8 pa0, bf16x8 pa1, bf16x8 pa2, bf16x8 pa3) {
;     pv_one<0>(o[0], vb, pa0, pa1, pa2, pa3); pv_one<1>(o[1], vb, pa0, pa1, pa2, pa3); pv_one<2>(o[2], vb, pa0, pa1, pa2, pa3); pv_one<3>(o[3], vb, pa0, pa1, pa2, pa3);
	v_mfma_f32_32x32x16_bf16 v[64:79], v[38:41], v[114:117], v[64:79]
	ds_read_b128 v[34:37], v31 offset:128
	ds_read_b128 v[38:41], v31 offset:12416
	s_waitcnt lgkmcnt(1)
	v_mfma_f32_32x32x16_bf16 v[80:95], v[34:37], v[110:113], v[80:95]
	s_waitcnt lgkmcnt(0)
	v_mfma_f32_32x32x16_bf16 v[64:79], v[38:41], v[110:113], v[64:79]
	ds_read_b128 v[34:37], v33 offset:128
	ds_read_b128 v[38:41], v33 offset:12416
	s_waitcnt lgkmcnt(1)
	v_mfma_f32_32x32x16_bf16 v[80:95], v[34:37], v[106:109], v[80:95]
	s_waitcnt lgkmcnt(0)
	v_mfma_f32_32x32x16_bf16 v[64:79], v[38:41], v[106:109], v[64:79]
	ds_read_b128 v[34:37], v46 offset:128
	ds_read_b128 v[38:41], v46 offset:12416
	s_waitcnt lgkmcnt(1)
	v_mfma_f32_32x32x16_bf16 v[80:95], v[34:37], v[102:105], v[80:95]
	s_waitcnt lgkmcnt(0)
	v_mfma_f32_32x32x16_bf16 v[64:79], v[38:41], v[102:105], v[64:79]
	ds_read_b128 v[34:37], v47 offset:128
	ds_read_b128 v[38:41], v47 offset:12416
	s_waitcnt lgkmcnt(1)
	v_mfma_f32_32x32x16_bf16 v[80:95], v[34:37], v[98:101], v[80:95]
	s_waitcnt lgkmcnt(0)
	v_mfma_f32_32x32x16_bf16 v[64:79], v[38:41], v[98:101], v[64:79]
	ds_read_b128 v[34:37], v31 offset:256
	ds_read_b128 v[38:41], v31 offset:12544
	ds_read_b128 v[42:45], v213
	v_exp_f32_e32 v31, v32
	v_add_f32_e32 v32, 0, v9
	v_add_f32_e32 v32, v11, v32
	v_add_f32_e32 v32, v12, v32
	v_add_f32_e32 v32, v13, v32
	v_add_f32_e32 v32, v14, v32
	s_waitcnt lgkmcnt(0)
	v_mfma_f32_32x32x16_bf16 v[80:95], v[34:37], v[42:45], v[80:95]
	v_add_f32_e32 v32, v15, v32
	v_add_f32_e32 v32, v8, v32
	v_add_f32_e32 v32, v10, v32
	v_add_f32_e32 v32, v3, v32
	v_add_f32_e32 v32, v5, v32
	v_add_f32_e32 v32, v6, v32
	v_add_f32_e32 v32, v7, v32
	v_mfma_f32_32x32x16_bf16 v[64:79], v[38:41], v[42:45], v[64:79]
	ds_read_b128 v[34:37], v33 offset:256
	ds_read_b128 v[38:41], v33 offset:12544
	ds_read_b128 v[42:45], v212
	v_add_f32_e32 v32, v0, v32
	v_add_f32_e32 v32, v1, v32
	v_add_f32_e32 v32, v2, v32
	v_add_f32_e32 v32, v4, v32
	v_add_f32_e32 v32, v26, v32
	v_add_f32_e32 v32, v27, v32
	s_waitcnt lgkmcnt(0)
	v_mfma_f32_32x32x16_bf16 v[80:95], v[34:37], v[42:45], v[80:95]
	v_add_f32_e32 v32, v28, v32
	v_add_f32_e32 v32, v29, v32
	v_add_f32_e32 v32, v30, v32
	v_add_f32_e32 v32, v19, v32
	v_add_f32_e32 v32, v20, v32
	v_add_f32_e32 v32, v21, v32
	v_add_f32_e32 v32, v22, v32
	v_mfma_f32_32x32x16_bf16 v[64:79], v[38:41], v[42:45], v[64:79]
	ds_read_b128 v[34:37], v46 offset:256
	ds_read_b128 v[38:41], v46 offset:12544
	ds_read_b128 v[42:45], v211
	v_add_f32_e32 v32, v23, v32
	v_add_f32_e32 v32, v24, v32
	v_add_f32_e32 v32, v25, v32
	v_add_f32_e32 v32, v16, v32
	v_add_f32_e32 v32, v17, v32
	v_add_f32_e32 v32, v18, v32
	s_waitcnt lgkmcnt(0)
	v_mfma_f32_32x32x16_bf16 v[80:95], v[34:37], v[42:45], v[80:95]
	v_add_f32_e32 v227, v31, v32
	v_mov_b32_e32 v228, v227
	s_nop 1
	v_permlane32_swap_b32_e32 v227, v228
	v_mfma_f32_32x32x16_bf16 v[64:79], v[38:41], v[42:45], v[64:79]
	ds_read_b128 v[34:37], v47 offset:256
	ds_read_b128 v[38:41], v47 offset:12544
	ds_read_b128 v[42:45], v210
	v_cvt_pk_bf16_f32 v48, v9, v11
	v_cvt_pk_bf16_f32 v49, v12, v13
	v_cvt_pk_bf16_f32 v50, v14, v15
	v_cvt_pk_bf16_f32 v51, v8, v10
	v_cvt_pk_bf16_f32 v138, v3, v5
	v_cvt_pk_bf16_f32 v139, v6, v7
	s_waitcnt lgkmcnt(0)
	v_mfma_f32_32x32x16_bf16 v[80:95], v[34:37], v[42:45], v[80:95]
	v_cvt_pk_bf16_f32 v140, v0, v1
	v_cvt_pk_bf16_f32 v141, v2, v4
	v_cvt_pk_bf16_f32 v142, v26, v27
	v_cvt_pk_bf16_f32 v143, v28, v29
	v_cvt_pk_bf16_f32 v144, v30, v19
	v_cvt_pk_bf16_f32 v145, v20, v21
	v_cvt_pk_bf16_f32 v170, v22, v23
	v_mfma_f32_32x32x16_bf16 v[64:79], v[38:41], v[42:45], v[64:79]
	v_cvt_pk_bf16_f32 v171, v24, v25
	v_cvt_pk_bf16_f32 v172, v16, v17
	v_permlane32_swap_b32_e32 v48, v50
	v_permlane32_swap_b32_e32 v49, v51
	v_permlane32_swap_b32_e32 v138, v140
	v_permlane32_swap_b32_e32 v139, v141
	v_permlane32_swap_b32_e32 v142, v144
	v_permlane32_swap_b32_e32 v143, v145
	v_cvt_pk_bf16_f32 v173, v18, v31
	v_permlane32_swap_b32_e32 v170, v172
	v_permlane32_swap_b32_e32 v171, v173
	ds_read_b64_tr_b16 v[0:1], v194 offset:0
	ds_read_b64_tr_b16 v[2:3], v194 offset:0x800
	ds_read_b64_tr_b16 v[16:17], v194 offset:0x1000
	ds_read_b64_tr_b16 v[18:19], v194 offset:0x1800
	ds_read_b64_tr_b16 v[20:21], v194 offset:0x2000
	ds_read_b64_tr_b16 v[22:23], v194 offset:0x2800
	ds_read_b64_tr_b16 v[24:25], v194 offset:0x3000
	ds_read_b64_tr_b16 v[26:27], v194 offset:0x3800
	s_waitcnt lgkmcnt(0)
	s_nop 0
	v_mfma_f32_32x32x16_bf16 v[0:15], v[48:51], v[0:3], 0
	v_mfma_f32_32x32x16_bf16 v[0:15], v[138:141], v[16:19], v[0:15]
	ds_read_b64_tr_b16 v[16:17], v194 offset:0x200
	ds_read_b64_tr_b16 v[18:19], v194 offset:0xa00
	ds_read_b64_tr_b16 v[32:33], v194 offset:0x1200
	ds_read_b64_tr_b16 v[34:35], v194 offset:0x1a00
	ds_read_b64_tr_b16 v[36:37], v194 offset:0x2200
	ds_read_b64_tr_b16 v[38:39], v194 offset:0x2a00
	ds_read_b64_tr_b16 v[40:41], v194 offset:0x3200
	v_mfma_f32_32x32x16_bf16 v[0:15], v[142:145], v[20:23], v[0:15]
	ds_read_b64_tr_b16 v[42:43], v194 offset:0x3a00
	s_waitcnt lgkmcnt(0)
; #define SBAR() __builtin_amdgcn_sched_barrier(0)
; #define SLOAD(kt) do { SLOADV(kt); SLOADK(kt); } while (0)
; #define SWRITE(b) do { *(LAS bf16x8*)(V_lds + (b) * SHM_V + vst0) = vs0; *(LAS bf16x8*)(V_lds + (b) * SHM_V + vst0 + 8192) = vs1; \
;     *(LAS bf16x8*)(K_lds + (b) * SHM_K + kst0) = ks0; *(LAS bf16x8*)(K_lds + (b) * SHM_K + kst0 + 32 * 384) = ks1; *(LAS bf16x8*)(K_lds + (b) * SHM_K + krst) = ks2; } while (0)
; #define SWAIT() asm volatile("s_waitcnt vmcnt(0)" ::: "memory")
; #define RESC(a) do { if (__any((a) < 1.f)) { if (hi == 0) al_l[r32] = (a); asm volatile("s_waitcnt lgkmcnt(0)" ::: "memory"); \
;     _Pragma("unroll") for (int d = 0; d < 4; ++d) _Pragma("unroll") for (int r = 0; r < 16; ++r) o[d][r] *= al_l[crow(r, hi)]; } } while (0)
; __device__ __forceinline__ void partialSM(f32x16& p0, f32x16& p1, float& m_reg, float& mn, float& alpha) {
;     constexpr float C = SCALE * 1.4426950408889634f;
;     float pmax = p0[0];
; #pragma unroll
;     for (int r = 1; r < 16; ++r) pmax = fmaxf(pmax, p0[r]);
; #pragma unroll
;     for (int r = 0; r < 16; ++r) pmax = fmaxf(pmax, p1[r]);
;     { auto rr = __builtin_amdgcn_permlane32_swap(__float_as_uint(pmax), __float_as_uint(pmax), false, false);
;       pmax = fmaxf(__uint_as_float(rr[0]), __uint_as_float(rr[1])); }
;     if (__builtin_expect(__all(pmax - m_reg <= THR / SCALE), 1)) { mn = m_reg; alpha = 1.f; }
;     else { mn = fmaxf(m_reg, pmax); alpha = __builtin_amdgcn_exp2f((m_reg - mn) * C); m_reg = mn; }
; template <bool DIRECT> ...
;     ...
;         SBAR(); qkt(pB0, pB1, K_lds + kb * SHM_K, qr, qrp, qsw, kq, hi);
;         finishSM(pA0, pA1, alA, l_reg, pa0, pa1, pa2, pa3); SBAR();
;         pv_d0(o, vb0 + pb_ * SHM_V, pa0, pa1, pa2, pa3); partialSM(pB0, pB1, m_reg, mnB, alB);
;         SWAIT(); SWRITE(nb_); SLOAD(j + 2);
;         RESC(alB); __syncthreads(); kb = nb_; }
	v_mfma_f32_32x32x16_bf16 v[0:15], v[170:173], v[24:27], v[0:15]
	v_mfma_f32_32x32x16_bf16 v[16:31], v[48:51], v[16:19], 0
	v_mfma_f32_32x32x16_bf16 v[16:31], v[138:141], v[32:35], v[16:31]
	ds_read_b64_tr_b16 v[32:33], v194 offset:0x400
	ds_read_b64_tr_b16 v[34:35], v194 offset:0xc00
	ds_read_b64_tr_b16 v[52:53], v194 offset:0x1400
	ds_read_b64_tr_b16 v[54:55], v194 offset:0x1c00
	ds_read_b64_tr_b16 v[56:57], v194 offset:0x2400
	ds_read_b64_tr_b16 v[58:59], v194 offset:0x2c00
	ds_read_b64_tr_b16 v[60:61], v194 offset:0x3400
	v_mfma_f32_32x32x16_bf16 v[16:31], v[142:145], v[36:39], v[16:31]
	ds_read_b64_tr_b16 v[62:63], v194 offset:0x3c00
	s_waitcnt lgkmcnt(0)
	v_mfma_f32_32x32x16_bf16 v[16:31], v[170:173], v[40:43], v[16:31]
	v_mfma_f32_32x32x16_bf16 v[32:47], v[48:51], v[32:35], 0
	v_mfma_f32_32x32x16_bf16 v[32:47], v[138:141], v[52:55], v[32:47]
	ds_read_b64_tr_b16 v[52:53], v194 offset:0x600
	ds_read_b64_tr_b16 v[54:55], v194 offset:0xe00
	ds_read_b64_tr_b16 v[148:149], v194 offset:0x1600
	ds_read_b64_tr_b16 v[150:151], v194 offset:0x1e00
	ds_read_b64_tr_b16 v[152:153], v194 offset:0x2600
	ds_read_b64_tr_b16 v[154:155], v194 offset:0x2e00
	ds_read_b64_tr_b16 v[200:201], v194 offset:0x3600
	v_mfma_f32_32x32x16_bf16 v[32:47], v[142:145], v[56:59], v[32:47]
	ds_read_b64_tr_b16 v[202:203], v194 offset:0x3e00
	s_waitcnt lgkmcnt(0)
	v_mfma_f32_32x32x16_bf16 v[32:47], v[170:173], v[60:63], v[32:47]
	v_max_f32_e32 v56, v81, v81
	v_max_f32_e32 v57, v80, v80
	v_max_f32_e32 v56, v57, v56
	v_max3_f32 v56, v56, v82, v83
	v_max3_f32 v156, v56, v84, v85
	v_mfma_f32_32x32x16_bf16 v[48:63], v[48:51], v[52:55], 0
	v_max3_f32 v156, v156, v86, v87
	v_max3_f32 v156, v156, v88, v89
	v_max3_f32 v156, v156, v90, v91
	v_max3_f32 v156, v156, v92, v93
	v_max3_f32 v156, v156, v94, v95
	v_max3_f32 v156, v156, v64, v65
	v_max3_f32 v156, v156, v66, v67
	v_mfma_f32_32x32x16_bf16 v[48:63], v[138:141], v[148:151], v[48:63]
	v_max3_f32 v138, v156, v68, v69
	v_max3_f32 v138, v138, v70, v71
	v_max3_f32 v138, v138, v72, v73
	v_max3_f32 v138, v138, v74, v75
	v_max3_f32 v138, v138, v76, v77
	v_max3_f32 v138, v138, v78, v79
	v_mov_b32_e32 v139, v138
	s_nop 1
	v_permlane32_swap_b32_e32 v138, v139
	v_max_f32_e32 v139, v139, v139
	v_max_f32_e32 v138, v138, v138
	v_max_f32_e32 v138, v138, v139
	v_sub_f32_e32 v139, v138, v229
	v_cmp_ge_f32_e32 vcc, s14, v139
	s_cmp_eq_u64 vcc, exec
	s_cselect_b64 s[42:43], -1, 0
	s_addk_i32 s19, 0xc0
	v_mfma_f32_32x32x16_bf16 v[48:63], v[142:145], v[152:155], v[48:63]
	v_max_f32_e32 v231, v229, v138
	v_mad_i64_i32 v[142:143], s[20:21], s19, v220, v[146:147]
	v_sub_f32_e32 v138, v229, v231
	v_add_co_u32_e32 v150, vcc, 0x1c000, v142
	v_mul_f32_e32 v138, 0x3dd53b94, v138
	s_waitcnt vmcnt(0)
	s_nop 0
	v_addc_co_u32_e32 v151, vcc, 0, v143, vcc
	v_exp_f32_e32 v232, v138
	global_load_dwordx4 v[138:141], v[142:143], off offset:256
	s_nop 0
	global_load_dwordx4 v[142:145], v[142:143], off
	s_nop 0
	global_load_dwordx4 v[146:149], v[150:151], off offset:256
	s_nop 0
	global_load_dwordx4 v[150:153], v[150:151], off
	v_mad_i64_i32 v[154:155], s[20:21], s19, v218, v[176:177]
	global_load_dwordx4 v[154:157], v[154:155], off
	v_mfma_f32_32x32x16_bf16 v[48:63], v[170:173], v[200:203], v[48:63]
	s_add_i32 s19, 0, 0x18000
	v_cndmask_b32_e64 v170, v232, 1.0, s[42:43]
	s_waitcnt vmcnt(9)
	ds_write_b128 v208, v[130:133] offset:32768
	s_waitcnt vmcnt(8)
	ds_write_b128 v208, v[134:137] offset:40960
	v_add_u32_e32 v130, s19, v192
	s_waitcnt vmcnt(5)
	ds_write_b128 v130, v[166:169]
	ds_write_b128 v130, v[162:165] offset:12288
	v_add_u32_e32 v130, s19, v193
	v_cmp_gt_f32_e32 vcc, 1.0, v170
	ds_write_b128 v130, v[158:161]
	s_cbranch_vccz .LBB0_961
	s_and_saveexec_b64 s[46:47], s[38:39]
	ds_write_b32 v195, v170 offset:128
	s_or_b64 exec, exec, s[46:47]
	s_waitcnt lgkmcnt(0)
	v_add_u32_e32 v162, v181, v196
	ds_read_b128 v[130:133], v162 offset:224
	ds_read_b128 v[134:137], v162 offset:192
	ds_read_b128 v[158:161], v162 offset:160
	ds_read_b128 v[162:165], v162 offset:128
	s_waitcnt lgkmcnt(3)
	v_pk_mul_f32 v[12:13], v[12:13], v[130:131]
	s_waitcnt lgkmcnt(2)
	v_pk_mul_f32 v[8:9], v[8:9], v[134:135]
	s_waitcnt lgkmcnt(1)
	v_pk_mul_f32 v[4:5], v[4:5], v[158:159]
	v_pk_mul_f32 v[14:15], v[14:15], v[132:133]
	v_pk_mul_f32 v[10:11], v[10:11], v[136:137]
	v_pk_mul_f32 v[6:7], v[6:7], v[160:161]
	s_waitcnt lgkmcnt(0)
	v_pk_mul_f32 v[2:3], v[2:3], v[164:165]
	v_pk_mul_f32 v[0:1], v[0:1], v[162:163]
	v_pk_mul_f32 v[28:29], v[28:29], v[130:131]
	v_pk_mul_f32 v[24:25], v[24:25], v[134:135]
	v_pk_mul_f32 v[20:21], v[20:21], v[158:159]
	v_pk_mul_f32 v[30:31], v[30:31], v[132:133]
	v_pk_mul_f32 v[26:27], v[26:27], v[136:137]
	v_pk_mul_f32 v[22:23], v[22:23], v[160:161]
	v_pk_mul_f32 v[18:19], v[18:19], v[164:165]
	v_pk_mul_f32 v[16:17], v[16:17], v[162:163]
	v_pk_mul_f32 v[44:45], v[44:45], v[130:131]
	v_pk_mul_f32 v[40:41], v[40:41], v[134:135]
	v_pk_mul_f32 v[36:37], v[36:37], v[158:159]
	v_pk_mul_f32 v[46:47], v[46:47], v[132:133]
	v_pk_mul_f32 v[42:43], v[42:43], v[136:137]
	v_pk_mul_f32 v[38:39], v[38:39], v[160:161]
	v_pk_mul_f32 v[34:35], v[34:35], v[164:165]
	v_pk_mul_f32 v[32:33], v[32:33], v[162:163]
	v_pk_mul_f32 v[60:61], v[60:61], v[130:131]
	v_pk_mul_f32 v[56:57], v[56:57], v[134:135]
	v_pk_mul_f32 v[52:53], v[52:53], v[158:159]
	v_pk_mul_f32 v[62:63], v[62:63], v[132:133]
	v_pk_mul_f32 v[58:59], v[58:59], v[136:137]
	v_pk_mul_f32 v[54:55], v[54:55], v[160:161]
	v_pk_mul_f32 v[50:51], v[50:51], v[164:165]
	v_pk_mul_f32 v[48:49], v[48:49], v[162:163]
